# static s_setprio 1 for waves 0-3 during attention units (other half variant)
# speedup vs baseline: 1.0085x; 1.0085x over previous
; #define LAS __attribute__((address_space(3)))
; __device__ __forceinline__ void attn_unit(const Args& c, int l, int b, int h, int qb, float lam, float lam_init, LAS unsigned char* lds) {
;     ...
;     const int tid = tid_, lane = tid & 63, w = __builtin_amdgcn_readfirstlane(tid >> 6), r = lane & 15, q4 = lane >> 4;
;     LAS bf16* Kt = (LAS bf16*)lds;
;     LAS bf16* Vs = Kt + 128 * 136;
;     const bf16* P = ((bf16*)(wsl + WS_P));
;     const size_t seq0 = (size_t)b * T;
;     const int QC = DIFF_BASE + h * 128, KC = DIFF_BASE + 1024 + h * 128, VC = DIFF_BASE + 2048 + h * 128;
;     const float* qnw = c.in[22 + z_] + l * 64; const float* knw = c.in[23 + z_] + l * 64;
;     bf16x8 qf[2][2];
;     {
;         const bf16* qrow = P + (seq0 + 128 * qb + 16 * w + r) * PW + QC;
; __device__ __forceinline__ void m2_phase(const Args& c, int l, LAS unsigned char* lds, int G, int mode, bool dry, int cidx) {
;     ...
;             __syncthreads();
;             if (tid_ == 0) *slot = (int)atomicAdd(ctr, 1u);
;             __syncthreads();
;             const int q = *slot;
;             if (q >= 128) break;
;             const int qb = 15 - (q >> 3);
;             attn_unit(c, l, q & 7, qx, qb, lam, lam_init, lds);
.LBB0_243:
	s_or_b64 exec, exec, s[2:3]
	v_mov_b32_e32 v0, s39
	s_waitcnt lgkmcnt(0)
	s_barrier
	ds_read_b32 v0, v0
	s_movk_i32 s2, 0x7f
	s_waitcnt lgkmcnt(0)
	v_cmp_lt_i32_e32 vcc, s2, v0
	v_readfirstlane_b32 s4, v0
	s_mov_b64 s[2:3], -1
	s_cbranch_vccnz .LBB0_240
	v_readlane_b32 s8, v252, 57
	s_and_b32 s6, s4, 7
	s_lshr_b32 s7, s4, 6
	s_lshl_b32 s7, s7, 3
	s_add_i32 s6, s6, s7
	v_readlane_b32 s10, v252, 59
	v_readlane_b32 s11, v252, 60
	s_sub_i32 s22, 15, s6
	v_mov_b32_e32 v106, v179
	s_mov_b64 s[38:39], s[10:11]
	v_readlane_b32 s9, v252, 58
	s_mov_b32 s8, 0
	s_add_u32 s2, s38, 0xa800000
	s_addc_u32 s3, s39, 0
	s_lshl_b32 s4, s4, 8
	s_ashr_i32 s9, s8, 31
	s_and_b32 s18, s4, 0x3800
	s_lshl_b64 s[4:5], s[8:9], 3
	v_readlane_b32 s8, v251, 0
	v_readlane_b32 s9, v251, 1
	s_add_u32 s24, s8, s4
	s_addc_u32 s25, s9, s5
	s_load_dwordx4 s[8:11], s[24:25], 0xb0
	v_readfirstlane_b32 s4, v106
	v_and_b32_e32 v107, 15, v106
	v_mov_b64_e32 v[18:19], s[2:3]
	v_bfe_u32 v108, v106, 4, 2
	s_waitcnt lgkmcnt(0)
	s_cmp_lt_u32 s4, 0x100
	s_cbranch_scc0 .Lattn_prio_skip
	s_setprio 1
